# m1 cache-conversion job: 16 loads issued up front with counted waits instead of 8 serialized load-wait-store iterations
# speedup vs baseline: 1.0320x; 1.0058x over previous
.LBB0_295:
	s_mov_b64 s[4:5], 0x4000
	s_mov_b64 s[2:3], 0x2000
	global_load_dwordx4 v[14:17], v[0:1], off
	global_load_dwordx4 v[18:21], v[0:1], off offset:16
	v_lshl_add_u64 v[0:1], v[0:1], 0, s[4:5]
	global_load_dwordx4 v[22:25], v[0:1], off
	global_load_dwordx4 v[26:29], v[0:1], off offset:16
	v_lshl_add_u64 v[0:1], v[0:1], 0, s[4:5]
	global_load_dwordx4 v[30:33], v[0:1], off
	global_load_dwordx4 v[34:37], v[0:1], off offset:16
	v_lshl_add_u64 v[0:1], v[0:1], 0, s[4:5]
	global_load_dwordx4 v[38:41], v[0:1], off
	global_load_dwordx4 v[42:45], v[0:1], off offset:16
	v_lshl_add_u64 v[0:1], v[0:1], 0, s[4:5]
	global_load_dwordx4 v[46:49], v[0:1], off
	global_load_dwordx4 v[50:53], v[0:1], off offset:16
	v_lshl_add_u64 v[0:1], v[0:1], 0, s[4:5]
	global_load_dwordx4 v[54:57], v[0:1], off
	global_load_dwordx4 v[58:61], v[0:1], off offset:16
	v_lshl_add_u64 v[0:1], v[0:1], 0, s[4:5]
	global_load_dwordx4 v[62:65], v[0:1], off
	global_load_dwordx4 v[66:69], v[0:1], off offset:16
	v_lshl_add_u64 v[0:1], v[0:1], 0, s[4:5]
	global_load_dwordx4 v[70:73], v[0:1], off
	global_load_dwordx4 v[74:77], v[0:1], off offset:16
	v_lshl_add_u64 v[0:1], v[0:1], 0, s[4:5]
	s_waitcnt vmcnt(14)
	v_cvt_pk_bf16_f32 v14, v14, v15
	v_cvt_pk_bf16_f32 v15, v16, v17
	v_cvt_pk_bf16_f32 v16, v18, v19
	v_cvt_pk_bf16_f32 v17, v20, v21
	global_store_dwordx4 v[2:3], v[14:17], off
	v_lshl_add_u64 v[2:3], v[2:3], 0, s[2:3]
	s_waitcnt vmcnt(13)
	v_cvt_pk_bf16_f32 v22, v22, v23
	v_cvt_pk_bf16_f32 v23, v24, v25
	v_cvt_pk_bf16_f32 v24, v26, v27
	v_cvt_pk_bf16_f32 v25, v28, v29
	global_store_dwordx4 v[2:3], v[22:25], off
	v_lshl_add_u64 v[2:3], v[2:3], 0, s[2:3]
	s_waitcnt vmcnt(12)
	v_cvt_pk_bf16_f32 v30, v30, v31
	v_cvt_pk_bf16_f32 v31, v32, v33
	v_cvt_pk_bf16_f32 v32, v34, v35
	v_cvt_pk_bf16_f32 v33, v36, v37
	global_store_dwordx4 v[2:3], v[30:33], off
	v_lshl_add_u64 v[2:3], v[2:3], 0, s[2:3]
	s_waitcnt vmcnt(11)
	v_cvt_pk_bf16_f32 v38, v38, v39
	v_cvt_pk_bf16_f32 v39, v40, v41
	v_cvt_pk_bf16_f32 v40, v42, v43
	v_cvt_pk_bf16_f32 v41, v44, v45
	global_store_dwordx4 v[2:3], v[38:41], off
	v_lshl_add_u64 v[2:3], v[2:3], 0, s[2:3]
	s_waitcnt vmcnt(10)
	v_cvt_pk_bf16_f32 v46, v46, v47
	v_cvt_pk_bf16_f32 v47, v48, v49
	v_cvt_pk_bf16_f32 v48, v50, v51
	v_cvt_pk_bf16_f32 v49, v52, v53
	global_store_dwordx4 v[2:3], v[46:49], off
	v_lshl_add_u64 v[2:3], v[2:3], 0, s[2:3]
	s_waitcnt vmcnt(9)
	v_cvt_pk_bf16_f32 v54, v54, v55
	v_cvt_pk_bf16_f32 v55, v56, v57
	v_cvt_pk_bf16_f32 v56, v58, v59
	v_cvt_pk_bf16_f32 v57, v60, v61
	global_store_dwordx4 v[2:3], v[54:57], off
	v_lshl_add_u64 v[2:3], v[2:3], 0, s[2:3]
	s_waitcnt vmcnt(8)
	v_cvt_pk_bf16_f32 v62, v62, v63
	v_cvt_pk_bf16_f32 v63, v64, v65
	v_cvt_pk_bf16_f32 v64, v66, v67
	v_cvt_pk_bf16_f32 v65, v68, v69
	global_store_dwordx4 v[2:3], v[62:65], off
	v_lshl_add_u64 v[2:3], v[2:3], 0, s[2:3]
	s_waitcnt vmcnt(7)
	v_cvt_pk_bf16_f32 v70, v70, v71
	v_cvt_pk_bf16_f32 v71, v72, v73
	v_cvt_pk_bf16_f32 v72, v74, v75
	v_cvt_pk_bf16_f32 v73, v76, v77
	global_store_dwordx4 v[2:3], v[70:73], off
	v_lshl_add_u64 v[2:3], v[2:3], 0, s[2:3]
